# comb5 + no PART prefetch when the next FFN-in unit shares the row tile (rstd table in LDS stays valid)
# baseline (speedup 1.0000x reference)
; __device__ __forceinline__ unsigned cvt_pk_bf16(float lo, float hi) { unsigned r; asm volatile("v_cvt_pk_bf16_f32 %0, %1, %2" : "=v"(r) : "v"(lo), "v"(hi)); return r; }
; __device__ __forceinline__ float sigmoidf_(float x) { return fast_rcp(1.0f + fast_exp2(-1.4426950408889634f * x)); }
;     __device__ __forceinline__ void operator()(const f32x4 (&acc)[2][2][4][2], const Unit& u, int wr, int wc, int fr, int fq) const {
;     ...
;             for (int m = 0; m < 4; ++m) { const float sc = rs[ai][m]; f32x4 o[2];
; #pragma unroll
;                 for (int n = 0; n < 2; ++n) { const f32x4 g = acc[ai][0][m][n] * sc, up = acc[ai][1][m][n] * sc;
; #pragma unroll
;                     for (int e = 0; e < 4; ++e) o[n][e] = g[e] * sigmoidf_(g[e]) * up[e]; }
;                 u32x4 w; w.x = cvt_pk_bf16(o[0][0], o[0][1]); w.y = cvt_pk_bf16(o[0][2], o[0][3]); w.z = cvt_pk_bf16(o[1][0], o[1][1]); w.w = cvt_pk_bf16(o[1][2], o[1][3]);
;                 *(u32x4*)(O + (size_t)(row0 + ai * HALF + m * 16) * FF + col0) = w; }
.Lswg_go_SWG_LBB0_264:
	s_cmp_lg_u64 s[2:3], 0
	s_cbranch_scc0 .Lswg_np_SWG_LBB0_264
	s_cmp_eq_u32 s91, s11
	s_cbranch_scc1 .Lswg_np_SWG_LBB0_264
	v_lshrrev_b32_e32 v216, 1, v220
	s_lshl_b32 s96, s91, 8
	s_lshl_b32 s97, s95, 5
	s_add_i32 s96, s96, s97
	v_add_u32_e32 v216, s96, v216
	v_and_b32_e32 v217, 1, v220
	v_lshlrev_b32_e32 v217, 6, v217
	v_lshl_add_u32 v216, v216, 7, v217
	s_add_u32 s96, s14, 0xc300000
	s_addc_u32 s97, s15, 0
	global_load_dwordx4 v[200:203], v216, s[96:97]
	global_load_dwordx4 v[204:207], v216, s[96:97] offset:16
	global_load_dwordx4 v[208:211], v216, s[96:97] offset:32
	global_load_dwordx4 v[212:215], v216, s[96:97] offset:48
.Lswg_np_SWG_LBB0_264:
	v_pk_mul_f32 v[124:125], v[124:125], v[178:179] op_sel_hi:[1,0]
	v_pk_mul_f32 v[126:127], v[126:127], v[178:179] op_sel_hi:[1,0]
	v_pk_mul_f32 v[116:117], v[116:117], v[178:179] op_sel_hi:[1,0]
	v_pk_mul_f32 v[118:119], v[118:119], v[178:179] op_sel_hi:[1,0]
	v_pk_mul_f32 v[108:109], v[108:109], v[234:235] op_sel_hi:[1,0]
	v_pk_mul_f32 v[110:111], v[110:111], v[234:235] op_sel_hi:[1,0]
	v_pk_mul_f32 v[100:101], v[100:101], v[234:235] op_sel_hi:[1,0]
	v_pk_mul_f32 v[102:103], v[102:103], v[234:235] op_sel_hi:[1,0]
	v_pk_mul_f32 v[128:129], v[124:125], v[248:249] op_sel_hi:[1,0]
	v_pk_mul_f32 v[130:131], v[126:127], v[248:249] op_sel_hi:[1,0]
	v_pk_mul_f32 v[132:133], v[116:117], v[248:249] op_sel_hi:[1,0]
	v_pk_mul_f32 v[134:135], v[118:119], v[248:249] op_sel_hi:[1,0]
	v_pk_mul_f32 v[162:163], v[108:109], v[248:249] op_sel_hi:[1,0]
	v_pk_mul_f32 v[164:165], v[110:111], v[248:249] op_sel_hi:[1,0]
	v_pk_mul_f32 v[166:167], v[100:101], v[248:249] op_sel_hi:[1,0]
	v_pk_mul_f32 v[168:169], v[102:103], v[248:249] op_sel_hi:[1,0]
	v_exp_f32_e32 v128, v128
	v_exp_f32_e32 v129, v129
	v_exp_f32_e32 v130, v130
	v_exp_f32_e32 v131, v131
	v_exp_f32_e32 v132, v132
	v_exp_f32_e32 v133, v133
	v_exp_f32_e32 v134, v134
	v_exp_f32_e32 v135, v135
	v_exp_f32_e32 v162, v162
	v_exp_f32_e32 v163, v163
	v_exp_f32_e32 v164, v164
	v_exp_f32_e32 v165, v165
	v_exp_f32_e32 v166, v166
	v_exp_f32_e32 v167, v167
	v_exp_f32_e32 v168, v168
	v_exp_f32_e32 v169, v169
	v_pk_mul_f32 v[120:121], v[120:121], v[178:179] op_sel_hi:[1,0]
	v_pk_mul_f32 v[122:123], v[122:123], v[178:179] op_sel_hi:[1,0]
	v_pk_mul_f32 v[112:113], v[112:113], v[178:179] op_sel_hi:[1,0]
	v_pk_mul_f32 v[114:115], v[114:115], v[178:179] op_sel_hi:[1,0]
	v_pk_mul_f32 v[104:105], v[104:105], v[234:235] op_sel_hi:[1,0]
	v_pk_mul_f32 v[106:107], v[106:107], v[234:235] op_sel_hi:[1,0]
	v_pk_mul_f32 v[96:97], v[96:97], v[234:235] op_sel_hi:[1,0]
	v_pk_mul_f32 v[98:99], v[98:99], v[234:235] op_sel_hi:[1,0]
	v_pk_add_f32 v[128:129], v[128:129], 1.0 op_sel_hi:[1,0]
	v_pk_add_f32 v[130:131], v[130:131], 1.0 op_sel_hi:[1,0]
	v_pk_add_f32 v[132:133], v[132:133], 1.0 op_sel_hi:[1,0]
	v_pk_add_f32 v[134:135], v[134:135], 1.0 op_sel_hi:[1,0]
	v_pk_add_f32 v[162:163], v[162:163], 1.0 op_sel_hi:[1,0]
	v_pk_add_f32 v[164:165], v[164:165], 1.0 op_sel_hi:[1,0]
	v_pk_add_f32 v[166:167], v[166:167], 1.0 op_sel_hi:[1,0]
	v_pk_add_f32 v[168:169], v[168:169], 1.0 op_sel_hi:[1,0]
	v_rcp_f32_e32 v128, v128
	v_rcp_f32_e32 v129, v129
	v_rcp_f32_e32 v130, v130
	v_rcp_f32_e32 v131, v131
	v_rcp_f32_e32 v132, v132
	v_rcp_f32_e32 v133, v133
	v_rcp_f32_e32 v134, v134
	v_rcp_f32_e32 v135, v135
	v_rcp_f32_e32 v162, v162
	v_rcp_f32_e32 v163, v163
	v_rcp_f32_e32 v164, v164
	v_rcp_f32_e32 v165, v165
	v_rcp_f32_e32 v166, v166
	v_rcp_f32_e32 v167, v167
	v_rcp_f32_e32 v168, v168
	v_rcp_f32_e32 v169, v169
	v_mov_b32_e32 v140, v251
	v_add_u32_e32 v174, 0x2c000, v251
	v_pk_mul_f32 v[124:125], v[124:125], v[128:129]
	v_pk_mul_f32 v[126:127], v[126:127], v[130:131]
	v_pk_mul_f32 v[116:117], v[116:117], v[132:133]
	v_pk_mul_f32 v[118:119], v[118:119], v[134:135]
	v_pk_mul_f32 v[108:109], v[108:109], v[162:163]
	v_pk_mul_f32 v[110:111], v[110:111], v[164:165]
	v_pk_mul_f32 v[100:101], v[100:101], v[166:167]
	v_pk_mul_f32 v[102:103], v[102:103], v[168:169]
	v_pk_mul_f32 v[124:125], v[124:125], v[120:121]
	v_pk_mul_f32 v[126:127], v[126:127], v[122:123]
	v_pk_mul_f32 v[116:117], v[116:117], v[112:113]
	v_pk_mul_f32 v[118:119], v[118:119], v[114:115]
	v_pk_mul_f32 v[108:109], v[108:109], v[104:105]
	v_pk_mul_f32 v[110:111], v[110:111], v[106:107]
	v_pk_mul_f32 v[100:101], v[100:101], v[96:97]
	v_pk_mul_f32 v[102:103], v[102:103], v[98:99]
	v_cvt_pk_bf16_f32 v136, v124, v125
	v_cvt_pk_bf16_f32 v137, v126, v127
	v_cvt_pk_bf16_f32 v138, v116, v117
	v_cvt_pk_bf16_f32 v139, v118, v119
	v_cvt_pk_bf16_f32 v170, v108, v109
	v_cvt_pk_bf16_f32 v171, v110, v111
	v_cvt_pk_bf16_f32 v172, v100, v101
	v_cvt_pk_bf16_f32 v173, v102, v103
	global_store_dwordx4 v140, v[136:139], s[28:29]
	global_store_dwordx4 v174, v[170:173], s[28:29]
	s_nop 1
	v_pk_mul_f32 v[92:93], v[92:93], v[236:237] op_sel_hi:[1,0]
	v_pk_mul_f32 v[94:95], v[94:95], v[236:237] op_sel_hi:[1,0]
	v_pk_mul_f32 v[84:85], v[84:85], v[236:237] op_sel_hi:[1,0]
	v_pk_mul_f32 v[86:87], v[86:87], v[236:237] op_sel_hi:[1,0]
	v_pk_mul_f32 v[76:77], v[76:77], v[238:239] op_sel_hi:[1,0]
	v_pk_mul_f32 v[78:79], v[78:79], v[238:239] op_sel_hi:[1,0]
	v_pk_mul_f32 v[68:69], v[68:69], v[238:239] op_sel_hi:[1,0]
	v_pk_mul_f32 v[70:71], v[70:71], v[238:239] op_sel_hi:[1,0]
	v_pk_mul_f32 v[128:129], v[92:93], v[248:249] op_sel_hi:[1,0]
	v_pk_mul_f32 v[130:131], v[94:95], v[248:249] op_sel_hi:[1,0]
	v_pk_mul_f32 v[132:133], v[84:85], v[248:249] op_sel_hi:[1,0]
	v_pk_mul_f32 v[134:135], v[86:87], v[248:249] op_sel_hi:[1,0]
	v_pk_mul_f32 v[162:163], v[76:77], v[248:249] op_sel_hi:[1,0]
	v_pk_mul_f32 v[164:165], v[78:79], v[248:249] op_sel_hi:[1,0]
; __device__ __forceinline__ unsigned cvt_pk_bf16(float lo, float hi) { unsigned r; asm volatile("v_cvt_pk_bf16_f32 %0, %1, %2" : "=v"(r) : "v"(lo), "v"(hi)); return r; }
; __device__ __forceinline__ float sigmoidf_(float x) { return fast_rcp(1.0f + fast_exp2(-1.4426950408889634f * x)); }
;     __device__ __forceinline__ void operator()(const f32x4 (&acc)[2][2][4][2], const Unit& u, int wr, int wc, int fr, int fq) const {
;     ...
;             for (int m = 0; m < 4; ++m) { const float sc = rs[ai][m]; f32x4 o[2];
; #pragma unroll
;                 for (int n = 0; n < 2; ++n) { const f32x4 g = acc[ai][0][m][n] * sc, up = acc[ai][1][m][n] * sc;
; #pragma unroll
;                     for (int e = 0; e < 4; ++e) o[n][e] = g[e] * sigmoidf_(g[e]) * up[e]; }
;                 u32x4 w; w.x = cvt_pk_bf16(o[0][0], o[0][1]); w.y = cvt_pk_bf16(o[0][2], o[0][3]); w.z = cvt_pk_bf16(o[1][0], o[1][1]); w.w = cvt_pk_bf16(o[1][2], o[1][3]);
;                 *(u32x4*)(O + (size_t)(row0 + ai * HALF + m * 16) * FF + col0) = w; }
	v_pk_mul_f32 v[166:167], v[68:69], v[248:249] op_sel_hi:[1,0]
	v_pk_mul_f32 v[168:169], v[70:71], v[248:249] op_sel_hi:[1,0]
	v_exp_f32_e32 v128, v128
	v_exp_f32_e32 v129, v129
	v_exp_f32_e32 v130, v130
	v_exp_f32_e32 v131, v131
	v_exp_f32_e32 v132, v132
	v_exp_f32_e32 v133, v133
	v_exp_f32_e32 v134, v134
	v_exp_f32_e32 v135, v135
	v_exp_f32_e32 v162, v162
	v_exp_f32_e32 v163, v163
	v_exp_f32_e32 v164, v164
	v_exp_f32_e32 v165, v165
	v_exp_f32_e32 v166, v166
	v_exp_f32_e32 v167, v167
	v_exp_f32_e32 v168, v168
	v_exp_f32_e32 v169, v169
	v_pk_mul_f32 v[88:89], v[88:89], v[236:237] op_sel_hi:[1,0]
	v_pk_mul_f32 v[90:91], v[90:91], v[236:237] op_sel_hi:[1,0]
	v_pk_mul_f32 v[80:81], v[80:81], v[236:237] op_sel_hi:[1,0]
	v_pk_mul_f32 v[82:83], v[82:83], v[236:237] op_sel_hi:[1,0]
	v_pk_mul_f32 v[72:73], v[72:73], v[238:239] op_sel_hi:[1,0]
	v_pk_mul_f32 v[74:75], v[74:75], v[238:239] op_sel_hi:[1,0]
	v_pk_mul_f32 v[64:65], v[64:65], v[238:239] op_sel_hi:[1,0]
	v_pk_mul_f32 v[66:67], v[66:67], v[238:239] op_sel_hi:[1,0]
	v_pk_add_f32 v[128:129], v[128:129], 1.0 op_sel_hi:[1,0]
	v_pk_add_f32 v[130:131], v[130:131], 1.0 op_sel_hi:[1,0]
	v_pk_add_f32 v[132:133], v[132:133], 1.0 op_sel_hi:[1,0]
	v_pk_add_f32 v[134:135], v[134:135], 1.0 op_sel_hi:[1,0]
	v_pk_add_f32 v[162:163], v[162:163], 1.0 op_sel_hi:[1,0]
	v_pk_add_f32 v[164:165], v[164:165], 1.0 op_sel_hi:[1,0]
	v_pk_add_f32 v[166:167], v[166:167], 1.0 op_sel_hi:[1,0]
	v_pk_add_f32 v[168:169], v[168:169], 1.0 op_sel_hi:[1,0]
	v_rcp_f32_e32 v128, v128
	v_rcp_f32_e32 v129, v129
	v_rcp_f32_e32 v130, v130
	v_rcp_f32_e32 v131, v131
	v_rcp_f32_e32 v132, v132
	v_rcp_f32_e32 v133, v133
	v_rcp_f32_e32 v134, v134
	v_rcp_f32_e32 v135, v135
	v_rcp_f32_e32 v162, v162
	v_rcp_f32_e32 v163, v163
	v_rcp_f32_e32 v164, v164
	v_rcp_f32_e32 v165, v165
	v_rcp_f32_e32 v166, v166
	v_rcp_f32_e32 v167, v167
	v_rcp_f32_e32 v168, v168
	v_rcp_f32_e32 v169, v169
	v_add_u32_e32 v140, 0x58000, v251
	v_add_u32_e32 v174, 0x84000, v251
	v_pk_mul_f32 v[92:93], v[92:93], v[128:129]
	v_pk_mul_f32 v[94:95], v[94:95], v[130:131]
	v_pk_mul_f32 v[84:85], v[84:85], v[132:133]
	v_pk_mul_f32 v[86:87], v[86:87], v[134:135]
	v_pk_mul_f32 v[76:77], v[76:77], v[162:163]
	v_pk_mul_f32 v[78:79], v[78:79], v[164:165]
	v_pk_mul_f32 v[68:69], v[68:69], v[166:167]
	v_pk_mul_f32 v[70:71], v[70:71], v[168:169]
	v_pk_mul_f32 v[92:93], v[92:93], v[88:89]
	v_pk_mul_f32 v[94:95], v[94:95], v[90:91]
	v_pk_mul_f32 v[84:85], v[84:85], v[80:81]
	v_pk_mul_f32 v[86:87], v[86:87], v[82:83]
	v_pk_mul_f32 v[76:77], v[76:77], v[72:73]
	v_pk_mul_f32 v[78:79], v[78:79], v[74:75]
	v_pk_mul_f32 v[68:69], v[68:69], v[64:65]
	v_pk_mul_f32 v[70:71], v[70:71], v[66:67]
	v_cvt_pk_bf16_f32 v136, v92, v93
	v_cvt_pk_bf16_f32 v137, v94, v95
	v_cvt_pk_bf16_f32 v138, v84, v85
	v_cvt_pk_bf16_f32 v139, v86, v87
	v_cvt_pk_bf16_f32 v170, v76, v77
	v_cvt_pk_bf16_f32 v171, v78, v79
	v_cvt_pk_bf16_f32 v172, v68, v69
	v_cvt_pk_bf16_f32 v173, v70, v71
	global_store_dwordx4 v140, v[136:139], s[28:29]
	global_store_dwordx4 v174, v[170:173], s[28:29]
	s_nop 1
	v_pk_mul_f32 v[60:61], v[60:61], v[240:241] op_sel_hi:[1,0]
	v_pk_mul_f32 v[62:63], v[62:63], v[240:241] op_sel_hi:[1,0]
	v_pk_mul_f32 v[52:53], v[52:53], v[240:241] op_sel_hi:[1,0]
	v_pk_mul_f32 v[54:55], v[54:55], v[240:241] op_sel_hi:[1,0]
	v_pk_mul_f32 v[44:45], v[44:45], v[242:243] op_sel_hi:[1,0]
	v_pk_mul_f32 v[46:47], v[46:47], v[242:243] op_sel_hi:[1,0]
	v_pk_mul_f32 v[36:37], v[36:37], v[242:243] op_sel_hi:[1,0]
	v_pk_mul_f32 v[38:39], v[38:39], v[242:243] op_sel_hi:[1,0]
	v_pk_mul_f32 v[128:129], v[60:61], v[248:249] op_sel_hi:[1,0]
	v_pk_mul_f32 v[130:131], v[62:63], v[248:249] op_sel_hi:[1,0]
	v_pk_mul_f32 v[132:133], v[52:53], v[248:249] op_sel_hi:[1,0]
	v_pk_mul_f32 v[134:135], v[54:55], v[248:249] op_sel_hi:[1,0]
	v_pk_mul_f32 v[162:163], v[44:45], v[248:249] op_sel_hi:[1,0]
	v_pk_mul_f32 v[164:165], v[46:47], v[248:249] op_sel_hi:[1,0]
	v_pk_mul_f32 v[166:167], v[36:37], v[248:249] op_sel_hi:[1,0]
	v_pk_mul_f32 v[168:169], v[38:39], v[248:249] op_sel_hi:[1,0]
	v_exp_f32_e32 v128, v128
	v_exp_f32_e32 v129, v129
	v_exp_f32_e32 v130, v130
	v_exp_f32_e32 v131, v131
	v_exp_f32_e32 v132, v132
	v_exp_f32_e32 v133, v133
	v_exp_f32_e32 v134, v134
	v_exp_f32_e32 v135, v135
	v_exp_f32_e32 v162, v162
	v_exp_f32_e32 v163, v163
	v_exp_f32_e32 v164, v164
	v_exp_f32_e32 v165, v165
	v_exp_f32_e32 v166, v166
	v_exp_f32_e32 v167, v167
	v_exp_f32_e32 v168, v168
	v_exp_f32_e32 v169, v169
	v_pk_mul_f32 v[56:57], v[56:57], v[240:241] op_sel_hi:[1,0]
	v_pk_mul_f32 v[58:59], v[58:59], v[240:241] op_sel_hi:[1,0]
	v_pk_mul_f32 v[48:49], v[48:49], v[240:241] op_sel_hi:[1,0]
	v_pk_mul_f32 v[50:51], v[50:51], v[240:241] op_sel_hi:[1,0]
	v_pk_mul_f32 v[40:41], v[40:41], v[242:243] op_sel_hi:[1,0]
	v_pk_mul_f32 v[42:43], v[42:43], v[242:243] op_sel_hi:[1,0]
	v_pk_mul_f32 v[32:33], v[32:33], v[242:243] op_sel_hi:[1,0]
	v_pk_mul_f32 v[34:35], v[34:35], v[242:243] op_sel_hi:[1,0]
	v_pk_add_f32 v[128:129], v[128:129], 1.0 op_sel_hi:[1,0]
	v_pk_add_f32 v[130:131], v[130:131], 1.0 op_sel_hi:[1,0]
	v_pk_add_f32 v[132:133], v[132:133], 1.0 op_sel_hi:[1,0]
	v_pk_add_f32 v[134:135], v[134:135], 1.0 op_sel_hi:[1,0]
	v_pk_add_f32 v[162:163], v[162:163], 1.0 op_sel_hi:[1,0]
	v_pk_add_f32 v[164:165], v[164:165], 1.0 op_sel_hi:[1,0]
	v_pk_add_f32 v[166:167], v[166:167], 1.0 op_sel_hi:[1,0]
	v_pk_add_f32 v[168:169], v[168:169], 1.0 op_sel_hi:[1,0]
	v_rcp_f32_e32 v128, v128
	v_rcp_f32_e32 v129, v129
	v_rcp_f32_e32 v130, v130
	v_rcp_f32_e32 v131, v131
	v_rcp_f32_e32 v132, v132
	v_rcp_f32_e32 v133, v133
	v_rcp_f32_e32 v134, v134
	v_rcp_f32_e32 v135, v135
; __device__ __forceinline__ unsigned cvt_pk_bf16(float lo, float hi) { unsigned r; asm volatile("v_cvt_pk_bf16_f32 %0, %1, %2" : "=v"(r) : "v"(lo), "v"(hi)); return r; }
; __device__ __forceinline__ float sigmoidf_(float x) { return fast_rcp(1.0f + fast_exp2(-1.4426950408889634f * x)); }
; __device__ __forceinline__ void load_rstd(const float* part, int row0, int fq, float (&rs)[2][4]) {
;     ...
;         for (int m = 0; m < 4; ++m) { const float* p = part + (size_t)(row0 + ai * HALF + m * 16) * NPART + fq * 8;
;             const f32x4 a = *(const f32x4*)p, b = *(const f32x4*)(p + 4); float s = ((a[0] + a[1]) + (a[2] + a[3])) + ((b[0] + b[1]) + (b[2] + b[3]));
;             s += __shfl_xor(s, 16); s += __shfl_xor(s, 32); rs[ai][m] = rsqrtf(s * (1.0f / D) + RMS_EPS); }
;     __device__ __forceinline__ void operator()(const f32x4 (&acc)[2][2][4][2], const Unit& u, int wr, int wc, int fr, int fq) const {
;     ...
;             for (int m = 0; m < 4; ++m) { const float sc = rs[ai][m]; f32x4 o[2];
; #pragma unroll
;                 for (int n = 0; n < 2; ++n) { const f32x4 g = acc[ai][0][m][n] * sc, up = acc[ai][1][m][n] * sc;
; #pragma unroll
;                     for (int e = 0; e < 4; ++e) o[n][e] = g[e] * sigmoidf_(g[e]) * up[e]; }
;                 u32x4 w; w.x = cvt_pk_bf16(o[0][0], o[0][1]); w.y = cvt_pk_bf16(o[0][2], o[0][3]); w.z = cvt_pk_bf16(o[1][0], o[1][1]); w.w = cvt_pk_bf16(o[1][2], o[1][3]);
;                 *(u32x4*)(O + (size_t)(row0 + ai * HALF + m * 16) * FF + col0) = w; }
	v_rcp_f32_e32 v162, v162
	v_rcp_f32_e32 v163, v163
	v_rcp_f32_e32 v164, v164
	v_rcp_f32_e32 v165, v165
	v_rcp_f32_e32 v166, v166
	v_rcp_f32_e32 v167, v167
	v_rcp_f32_e32 v168, v168
	v_rcp_f32_e32 v169, v169
	v_add_u32_e32 v140, 0x160000, v251
	v_add_u32_e32 v174, 0x18c000, v251
	v_pk_mul_f32 v[60:61], v[60:61], v[128:129]
	v_pk_mul_f32 v[62:63], v[62:63], v[130:131]
	v_pk_mul_f32 v[52:53], v[52:53], v[132:133]
	v_pk_mul_f32 v[54:55], v[54:55], v[134:135]
	v_pk_mul_f32 v[44:45], v[44:45], v[162:163]
	v_pk_mul_f32 v[46:47], v[46:47], v[164:165]
	v_pk_mul_f32 v[36:37], v[36:37], v[166:167]
	v_pk_mul_f32 v[38:39], v[38:39], v[168:169]
	v_pk_mul_f32 v[60:61], v[60:61], v[56:57]
	v_pk_mul_f32 v[62:63], v[62:63], v[58:59]
	v_pk_mul_f32 v[52:53], v[52:53], v[48:49]
	v_pk_mul_f32 v[54:55], v[54:55], v[50:51]
	v_pk_mul_f32 v[44:45], v[44:45], v[40:41]
	v_pk_mul_f32 v[46:47], v[46:47], v[42:43]
	v_pk_mul_f32 v[36:37], v[36:37], v[32:33]
	v_pk_mul_f32 v[38:39], v[38:39], v[34:35]
	v_cvt_pk_bf16_f32 v136, v60, v61
	v_cvt_pk_bf16_f32 v137, v62, v63
	v_cvt_pk_bf16_f32 v138, v52, v53
	v_cvt_pk_bf16_f32 v139, v54, v55
	v_cvt_pk_bf16_f32 v170, v44, v45
	v_cvt_pk_bf16_f32 v171, v46, v47
	v_cvt_pk_bf16_f32 v172, v36, v37
	v_cvt_pk_bf16_f32 v173, v38, v39
	global_store_dwordx4 v140, v[136:139], s[28:29]
	global_store_dwordx4 v174, v[170:173], s[28:29]
	s_nop 1
	v_pk_mul_f32 v[28:29], v[28:29], v[244:245] op_sel_hi:[1,0]
	v_pk_mul_f32 v[30:31], v[30:31], v[244:245] op_sel_hi:[1,0]
	v_pk_mul_f32 v[20:21], v[20:21], v[244:245] op_sel_hi:[1,0]
	v_pk_mul_f32 v[22:23], v[22:23], v[244:245] op_sel_hi:[1,0]
	v_pk_mul_f32 v[12:13], v[12:13], v[246:247] op_sel_hi:[1,0]
	v_pk_mul_f32 v[14:15], v[14:15], v[246:247] op_sel_hi:[1,0]
	v_pk_mul_f32 v[4:5], v[4:5], v[246:247] op_sel_hi:[1,0]
	v_pk_mul_f32 v[6:7], v[6:7], v[246:247] op_sel_hi:[1,0]
	v_pk_mul_f32 v[128:129], v[28:29], v[248:249] op_sel_hi:[1,0]
	v_pk_mul_f32 v[130:131], v[30:31], v[248:249] op_sel_hi:[1,0]
	v_pk_mul_f32 v[132:133], v[20:21], v[248:249] op_sel_hi:[1,0]
	v_pk_mul_f32 v[134:135], v[22:23], v[248:249] op_sel_hi:[1,0]
	v_pk_mul_f32 v[162:163], v[12:13], v[248:249] op_sel_hi:[1,0]
	v_pk_mul_f32 v[164:165], v[14:15], v[248:249] op_sel_hi:[1,0]
	v_pk_mul_f32 v[166:167], v[4:5], v[248:249] op_sel_hi:[1,0]
	v_pk_mul_f32 v[168:169], v[6:7], v[248:249] op_sel_hi:[1,0]
	v_exp_f32_e32 v128, v128
	v_exp_f32_e32 v129, v129
	v_exp_f32_e32 v130, v130
	v_exp_f32_e32 v131, v131
	v_exp_f32_e32 v132, v132
	v_exp_f32_e32 v133, v133
	v_exp_f32_e32 v134, v134
	v_exp_f32_e32 v135, v135
	v_exp_f32_e32 v162, v162
	v_exp_f32_e32 v163, v163
	v_exp_f32_e32 v164, v164
	v_exp_f32_e32 v165, v165
	v_exp_f32_e32 v166, v166
	v_exp_f32_e32 v167, v167
	v_exp_f32_e32 v168, v168
	v_exp_f32_e32 v169, v169
	v_pk_mul_f32 v[24:25], v[24:25], v[244:245] op_sel_hi:[1,0]
	v_pk_mul_f32 v[26:27], v[26:27], v[244:245] op_sel_hi:[1,0]
	v_pk_mul_f32 v[16:17], v[16:17], v[244:245] op_sel_hi:[1,0]
	v_pk_mul_f32 v[18:19], v[18:19], v[244:245] op_sel_hi:[1,0]
	v_pk_mul_f32 v[8:9], v[8:9], v[246:247] op_sel_hi:[1,0]
	v_pk_mul_f32 v[10:11], v[10:11], v[246:247] op_sel_hi:[1,0]
	v_pk_mul_f32 v[0:1], v[0:1], v[246:247] op_sel_hi:[1,0]
	v_pk_mul_f32 v[2:3], v[2:3], v[246:247] op_sel_hi:[1,0]
	v_pk_add_f32 v[128:129], v[128:129], 1.0 op_sel_hi:[1,0]
	v_pk_add_f32 v[130:131], v[130:131], 1.0 op_sel_hi:[1,0]
	v_pk_add_f32 v[132:133], v[132:133], 1.0 op_sel_hi:[1,0]
	v_pk_add_f32 v[134:135], v[134:135], 1.0 op_sel_hi:[1,0]
	v_pk_add_f32 v[162:163], v[162:163], 1.0 op_sel_hi:[1,0]
	v_pk_add_f32 v[164:165], v[164:165], 1.0 op_sel_hi:[1,0]
	v_pk_add_f32 v[166:167], v[166:167], 1.0 op_sel_hi:[1,0]
	v_pk_add_f32 v[168:169], v[168:169], 1.0 op_sel_hi:[1,0]
	v_rcp_f32_e32 v128, v128
	v_rcp_f32_e32 v129, v129
	v_rcp_f32_e32 v130, v130
	v_rcp_f32_e32 v131, v131
	v_rcp_f32_e32 v132, v132
	v_rcp_f32_e32 v133, v133
	v_rcp_f32_e32 v134, v134
	v_rcp_f32_e32 v135, v135
	v_rcp_f32_e32 v162, v162
	v_rcp_f32_e32 v163, v163
	v_rcp_f32_e32 v164, v164
	v_rcp_f32_e32 v165, v165
	v_rcp_f32_e32 v166, v166
	v_rcp_f32_e32 v167, v167
	v_rcp_f32_e32 v168, v168
	v_rcp_f32_e32 v169, v169
	v_add_u32_e32 v140, 0x1b8000, v251
	v_add_u32_e32 v174, 0x1e4000, v251
	v_pk_mul_f32 v[28:29], v[28:29], v[128:129]
	v_pk_mul_f32 v[30:31], v[30:31], v[130:131]
	v_pk_mul_f32 v[20:21], v[20:21], v[132:133]
	v_pk_mul_f32 v[22:23], v[22:23], v[134:135]
	v_pk_mul_f32 v[12:13], v[12:13], v[162:163]
	v_pk_mul_f32 v[14:15], v[14:15], v[164:165]
	v_pk_mul_f32 v[4:5], v[4:5], v[166:167]
	v_pk_mul_f32 v[6:7], v[6:7], v[168:169]
	v_pk_mul_f32 v[28:29], v[28:29], v[24:25]
	v_pk_mul_f32 v[30:31], v[30:31], v[26:27]
	v_pk_mul_f32 v[20:21], v[20:21], v[16:17]
	v_pk_mul_f32 v[22:23], v[22:23], v[18:19]
	v_pk_mul_f32 v[12:13], v[12:13], v[8:9]
	v_pk_mul_f32 v[14:15], v[14:15], v[10:11]
	v_pk_mul_f32 v[4:5], v[4:5], v[0:1]
	v_pk_mul_f32 v[6:7], v[6:7], v[2:3]
	v_cvt_pk_bf16_f32 v136, v28, v29
	v_cvt_pk_bf16_f32 v137, v30, v31
	v_cvt_pk_bf16_f32 v138, v20, v21
	v_cvt_pk_bf16_f32 v139, v22, v23
	v_cvt_pk_bf16_f32 v170, v12, v13
	v_cvt_pk_bf16_f32 v171, v14, v15
	v_cvt_pk_bf16_f32 v172, v4, v5
	v_cvt_pk_bf16_f32 v173, v6, v7
	global_store_dwordx4 v140, v[136:139], s[28:29]
	global_store_dwordx4 v174, v[170:173], s[28:29]
	s_cmp_lg_u64 s[2:3], 0
	s_cbranch_scc0 .Lswg_nf_SWG_LBB0_264
	s_cmp_eq_u32 s91, s11
	s_cbranch_scc1 .Lswg_end_SWG_LBB0_264
	s_waitcnt vmcnt(8)
	v_add_f32_e32 v200, v200, v201
	v_add_f32_e32 v202, v202, v203
	v_add_f32_e32 v204, v204, v205
	v_add_f32_e32 v206, v206, v207
	v_add_f32_e32 v208, v208, v209
	v_add_f32_e32 v210, v210, v211
	v_add_f32_e32 v212, v212, v213
	v_add_f32_e32 v214, v214, v215
	v_add_f32_e32 v200, v200, v202
	v_add_f32_e32 v204, v204, v206
	v_add_f32_e32 v208, v208, v210
	v_add_f32_e32 v212, v212, v214
	v_add_f32_e32 v200, v200, v204
	v_add_f32_e32 v208, v208, v212
	v_add_f32_e32 v200, v200, v208
	s_nop 1
	v_add_f32_dpp v204, v200, v200 quad_perm:[1,0,3,2] row_mask:0xf bank_mask:0xf
	v_fmamk_f32 v204, v204, 0x3a000000, v250
	v_rsq_f32_e32 v204, v204
	s_and_b32 s96, s99, 1
	s_xor_b32 s96, s96, 1
	s_lshl_b32 s96, s96, 10
	s_lshl_b32 s97, s95, 7
	s_add_i32 s96, s96, s97
	s_add_i32 s96, s96, 0x21000
	v_lshrrev_b32_e32 v216, 1, v220
	v_lshl_add_u32 v216, v216, 2, s96
	ds_write_b32 v216, v204
	s_and_b32 s99, s99, 1
	s_xor_b32 s99, s99, 3
	s_branch .Lswg_end_SWG_LBB0_264

; __device__ __forceinline__ unsigned cvt_pk_bf16(float lo, float hi) { unsigned r; asm volatile("v_cvt_pk_bf16_f32 %0, %1, %2" : "=v"(r) : "v"(lo), "v"(hi)); return r; }
; __device__ __forceinline__ float sigmoidf_(float x) { return fast_rcp(1.0f + fast_exp2(-1.4426950408889634f * x)); }
;     __device__ __forceinline__ void operator()(const f32x4 (&acc)[2][2][4][2], const Unit& u, int wr, int wc, int fr, int fq) const {
;     ...
;             for (int m = 0; m < 4; ++m) { const float sc = rs[ai][m]; f32x4 o[2];
; #pragma unroll
;                 for (int n = 0; n < 2; ++n) { const f32x4 g = acc[ai][0][m][n] * sc, up = acc[ai][1][m][n] * sc;
; #pragma unroll
;                     for (int e = 0; e < 4; ++e) o[n][e] = g[e] * sigmoidf_(g[e]) * up[e]; }
;                 u32x4 w; w.x = cvt_pk_bf16(o[0][0], o[0][1]); w.y = cvt_pk_bf16(o[0][2], o[0][3]); w.z = cvt_pk_bf16(o[1][0], o[1][1]); w.w = cvt_pk_bf16(o[1][2], o[1][3]);
;                 *(u32x4*)(O + (size_t)(row0 + ai * HALF + m * 16) * FF + col0) = w; }
.Lswg_go_SWG_LBB0_1151:
	s_cmp_lg_u64 s[2:3], 0
	s_cbranch_scc0 .Lswg_np_SWG_LBB0_1151
	s_cmp_eq_u32 s72, s11
	s_cbranch_scc1 .Lswg_np_SWG_LBB0_1151
	v_lshrrev_b32_e32 v204, 1, v220
	s_lshl_b32 s96, s72, 8
	s_lshl_b32 s97, s95, 5
	s_add_i32 s96, s96, s97
	v_add_u32_e32 v204, s96, v204
	v_and_b32_e32 v205, 1, v220
	v_lshlrev_b32_e32 v205, 6, v205
	v_lshl_add_u32 v204, v204, 7, v205
	s_add_u32 s96, s14, 0xc300000
	s_addc_u32 s97, s15, 0
	global_load_dwordx4 v[188:191], v204, s[96:97]
	global_load_dwordx4 v[192:195], v204, s[96:97] offset:16
	global_load_dwordx4 v[196:199], v204, s[96:97] offset:32
	global_load_dwordx4 v[200:203], v204, s[96:97] offset:48
.Lswg_np_SWG_LBB0_1151:
	v_pk_mul_f32 v[124:125], v[124:125], v[178:179] op_sel_hi:[1,0]
	v_pk_mul_f32 v[126:127], v[126:127], v[178:179] op_sel_hi:[1,0]
	v_pk_mul_f32 v[116:117], v[116:117], v[178:179] op_sel_hi:[1,0]
	v_pk_mul_f32 v[118:119], v[118:119], v[178:179] op_sel_hi:[1,0]
	v_pk_mul_f32 v[108:109], v[108:109], v[222:223] op_sel_hi:[1,0]
	v_pk_mul_f32 v[110:111], v[110:111], v[222:223] op_sel_hi:[1,0]
	v_pk_mul_f32 v[100:101], v[100:101], v[222:223] op_sel_hi:[1,0]
	v_pk_mul_f32 v[102:103], v[102:103], v[222:223] op_sel_hi:[1,0]
	v_pk_mul_f32 v[128:129], v[124:125], v[236:237] op_sel_hi:[1,0]
	v_pk_mul_f32 v[130:131], v[126:127], v[236:237] op_sel_hi:[1,0]
	v_pk_mul_f32 v[132:133], v[116:117], v[236:237] op_sel_hi:[1,0]
	v_pk_mul_f32 v[134:135], v[118:119], v[236:237] op_sel_hi:[1,0]
	v_pk_mul_f32 v[162:163], v[108:109], v[236:237] op_sel_hi:[1,0]
	v_pk_mul_f32 v[164:165], v[110:111], v[236:237] op_sel_hi:[1,0]
	v_pk_mul_f32 v[166:167], v[100:101], v[236:237] op_sel_hi:[1,0]
	v_pk_mul_f32 v[168:169], v[102:103], v[236:237] op_sel_hi:[1,0]
	v_exp_f32_e32 v128, v128
	v_exp_f32_e32 v129, v129
	v_exp_f32_e32 v130, v130
	v_exp_f32_e32 v131, v131
	v_exp_f32_e32 v132, v132
	v_exp_f32_e32 v133, v133
	v_exp_f32_e32 v134, v134
	v_exp_f32_e32 v135, v135
	v_exp_f32_e32 v162, v162
	v_exp_f32_e32 v163, v163
	v_exp_f32_e32 v164, v164
	v_exp_f32_e32 v165, v165
	v_exp_f32_e32 v166, v166
	v_exp_f32_e32 v167, v167
	v_exp_f32_e32 v168, v168
	v_exp_f32_e32 v169, v169
	v_pk_mul_f32 v[120:121], v[120:121], v[178:179] op_sel_hi:[1,0]
	v_pk_mul_f32 v[122:123], v[122:123], v[178:179] op_sel_hi:[1,0]
	v_pk_mul_f32 v[112:113], v[112:113], v[178:179] op_sel_hi:[1,0]
	v_pk_mul_f32 v[114:115], v[114:115], v[178:179] op_sel_hi:[1,0]
	v_pk_mul_f32 v[104:105], v[104:105], v[222:223] op_sel_hi:[1,0]
	v_pk_mul_f32 v[106:107], v[106:107], v[222:223] op_sel_hi:[1,0]
	v_pk_mul_f32 v[96:97], v[96:97], v[222:223] op_sel_hi:[1,0]
	v_pk_mul_f32 v[98:99], v[98:99], v[222:223] op_sel_hi:[1,0]
	v_pk_add_f32 v[128:129], v[128:129], 1.0 op_sel_hi:[1,0]
	v_pk_add_f32 v[130:131], v[130:131], 1.0 op_sel_hi:[1,0]
	v_pk_add_f32 v[132:133], v[132:133], 1.0 op_sel_hi:[1,0]
	v_pk_add_f32 v[134:135], v[134:135], 1.0 op_sel_hi:[1,0]
	v_pk_add_f32 v[162:163], v[162:163], 1.0 op_sel_hi:[1,0]
	v_pk_add_f32 v[164:165], v[164:165], 1.0 op_sel_hi:[1,0]
	v_pk_add_f32 v[166:167], v[166:167], 1.0 op_sel_hi:[1,0]
	v_pk_add_f32 v[168:169], v[168:169], 1.0 op_sel_hi:[1,0]
	v_rcp_f32_e32 v128, v128
	v_rcp_f32_e32 v129, v129
	v_rcp_f32_e32 v130, v130
	v_rcp_f32_e32 v131, v131
	v_rcp_f32_e32 v132, v132
	v_rcp_f32_e32 v133, v133
	v_rcp_f32_e32 v134, v134
	v_rcp_f32_e32 v135, v135
	v_rcp_f32_e32 v162, v162
	v_rcp_f32_e32 v163, v163
	v_rcp_f32_e32 v164, v164
	v_rcp_f32_e32 v165, v165
	v_rcp_f32_e32 v166, v166
	v_rcp_f32_e32 v167, v167
	v_rcp_f32_e32 v168, v168
	v_rcp_f32_e32 v169, v169
	v_mov_b32_e32 v140, v239
	v_add_u32_e32 v174, 0x2c000, v239
	v_pk_mul_f32 v[124:125], v[124:125], v[128:129]
	v_pk_mul_f32 v[126:127], v[126:127], v[130:131]
	v_pk_mul_f32 v[116:117], v[116:117], v[132:133]
	v_pk_mul_f32 v[118:119], v[118:119], v[134:135]
	v_pk_mul_f32 v[108:109], v[108:109], v[162:163]
	v_pk_mul_f32 v[110:111], v[110:111], v[164:165]
	v_pk_mul_f32 v[100:101], v[100:101], v[166:167]
	v_pk_mul_f32 v[102:103], v[102:103], v[168:169]
	v_pk_mul_f32 v[124:125], v[124:125], v[120:121]
	v_pk_mul_f32 v[126:127], v[126:127], v[122:123]
	v_pk_mul_f32 v[116:117], v[116:117], v[112:113]
	v_pk_mul_f32 v[118:119], v[118:119], v[114:115]
	v_pk_mul_f32 v[108:109], v[108:109], v[104:105]
	v_pk_mul_f32 v[110:111], v[110:111], v[106:107]
	v_pk_mul_f32 v[100:101], v[100:101], v[96:97]
	v_pk_mul_f32 v[102:103], v[102:103], v[98:99]
	v_cvt_pk_bf16_f32 v136, v124, v125
	v_cvt_pk_bf16_f32 v137, v126, v127
	v_cvt_pk_bf16_f32 v138, v116, v117
	v_cvt_pk_bf16_f32 v139, v118, v119
	v_cvt_pk_bf16_f32 v170, v108, v109
	v_cvt_pk_bf16_f32 v171, v110, v111
	v_cvt_pk_bf16_f32 v172, v100, v101
	v_cvt_pk_bf16_f32 v173, v102, v103
	global_store_dwordx4 v140, v[136:139], s[28:29]
	global_store_dwordx4 v174, v[170:173], s[28:29]
	s_nop 1
	v_pk_mul_f32 v[92:93], v[92:93], v[224:225] op_sel_hi:[1,0]
	v_pk_mul_f32 v[94:95], v[94:95], v[224:225] op_sel_hi:[1,0]
	v_pk_mul_f32 v[84:85], v[84:85], v[224:225] op_sel_hi:[1,0]
	v_pk_mul_f32 v[86:87], v[86:87], v[224:225] op_sel_hi:[1,0]
	v_pk_mul_f32 v[76:77], v[76:77], v[226:227] op_sel_hi:[1,0]
	v_pk_mul_f32 v[78:79], v[78:79], v[226:227] op_sel_hi:[1,0]
	v_pk_mul_f32 v[68:69], v[68:69], v[226:227] op_sel_hi:[1,0]
	v_pk_mul_f32 v[70:71], v[70:71], v[226:227] op_sel_hi:[1,0]
	v_pk_mul_f32 v[128:129], v[92:93], v[236:237] op_sel_hi:[1,0]
	v_pk_mul_f32 v[130:131], v[94:95], v[236:237] op_sel_hi:[1,0]
	v_pk_mul_f32 v[132:133], v[84:85], v[236:237] op_sel_hi:[1,0]
	v_pk_mul_f32 v[134:135], v[86:87], v[236:237] op_sel_hi:[1,0]
	v_pk_mul_f32 v[162:163], v[76:77], v[236:237] op_sel_hi:[1,0]
	v_pk_mul_f32 v[164:165], v[78:79], v[236:237] op_sel_hi:[1,0]
; __device__ __forceinline__ unsigned cvt_pk_bf16(float lo, float hi) { unsigned r; asm volatile("v_cvt_pk_bf16_f32 %0, %1, %2" : "=v"(r) : "v"(lo), "v"(hi)); return r; }
; __device__ __forceinline__ float sigmoidf_(float x) { return fast_rcp(1.0f + fast_exp2(-1.4426950408889634f * x)); }
;     __device__ __forceinline__ void operator()(const f32x4 (&acc)[2][2][4][2], const Unit& u, int wr, int wc, int fr, int fq) const {
;     ...
;             for (int m = 0; m < 4; ++m) { const float sc = rs[ai][m]; f32x4 o[2];
; #pragma unroll
;                 for (int n = 0; n < 2; ++n) { const f32x4 g = acc[ai][0][m][n] * sc, up = acc[ai][1][m][n] * sc;
; #pragma unroll
;                     for (int e = 0; e < 4; ++e) o[n][e] = g[e] * sigmoidf_(g[e]) * up[e]; }
;                 u32x4 w; w.x = cvt_pk_bf16(o[0][0], o[0][1]); w.y = cvt_pk_bf16(o[0][2], o[0][3]); w.z = cvt_pk_bf16(o[1][0], o[1][1]); w.w = cvt_pk_bf16(o[1][2], o[1][3]);
;                 *(u32x4*)(O + (size_t)(row0 + ai * HALF + m * 16) * FF + col0) = w; }
	v_pk_mul_f32 v[166:167], v[68:69], v[236:237] op_sel_hi:[1,0]
	v_pk_mul_f32 v[168:169], v[70:71], v[236:237] op_sel_hi:[1,0]
	v_exp_f32_e32 v128, v128
	v_exp_f32_e32 v129, v129
	v_exp_f32_e32 v130, v130
	v_exp_f32_e32 v131, v131
	v_exp_f32_e32 v132, v132
	v_exp_f32_e32 v133, v133
	v_exp_f32_e32 v134, v134
	v_exp_f32_e32 v135, v135
	v_exp_f32_e32 v162, v162
	v_exp_f32_e32 v163, v163
	v_exp_f32_e32 v164, v164
	v_exp_f32_e32 v165, v165
	v_exp_f32_e32 v166, v166
	v_exp_f32_e32 v167, v167
	v_exp_f32_e32 v168, v168
	v_exp_f32_e32 v169, v169
	v_pk_mul_f32 v[88:89], v[88:89], v[224:225] op_sel_hi:[1,0]
	v_pk_mul_f32 v[90:91], v[90:91], v[224:225] op_sel_hi:[1,0]
	v_pk_mul_f32 v[80:81], v[80:81], v[224:225] op_sel_hi:[1,0]
	v_pk_mul_f32 v[82:83], v[82:83], v[224:225] op_sel_hi:[1,0]
	v_pk_mul_f32 v[72:73], v[72:73], v[226:227] op_sel_hi:[1,0]
	v_pk_mul_f32 v[74:75], v[74:75], v[226:227] op_sel_hi:[1,0]
	v_pk_mul_f32 v[64:65], v[64:65], v[226:227] op_sel_hi:[1,0]
	v_pk_mul_f32 v[66:67], v[66:67], v[226:227] op_sel_hi:[1,0]
	v_pk_add_f32 v[128:129], v[128:129], 1.0 op_sel_hi:[1,0]
	v_pk_add_f32 v[130:131], v[130:131], 1.0 op_sel_hi:[1,0]
	v_pk_add_f32 v[132:133], v[132:133], 1.0 op_sel_hi:[1,0]
	v_pk_add_f32 v[134:135], v[134:135], 1.0 op_sel_hi:[1,0]
	v_pk_add_f32 v[162:163], v[162:163], 1.0 op_sel_hi:[1,0]
	v_pk_add_f32 v[164:165], v[164:165], 1.0 op_sel_hi:[1,0]
	v_pk_add_f32 v[166:167], v[166:167], 1.0 op_sel_hi:[1,0]
	v_pk_add_f32 v[168:169], v[168:169], 1.0 op_sel_hi:[1,0]
	v_rcp_f32_e32 v128, v128
	v_rcp_f32_e32 v129, v129
	v_rcp_f32_e32 v130, v130
	v_rcp_f32_e32 v131, v131
	v_rcp_f32_e32 v132, v132
	v_rcp_f32_e32 v133, v133
	v_rcp_f32_e32 v134, v134
	v_rcp_f32_e32 v135, v135
	v_rcp_f32_e32 v162, v162
	v_rcp_f32_e32 v163, v163
	v_rcp_f32_e32 v164, v164
	v_rcp_f32_e32 v165, v165
	v_rcp_f32_e32 v166, v166
	v_rcp_f32_e32 v167, v167
	v_rcp_f32_e32 v168, v168
	v_rcp_f32_e32 v169, v169
	v_add_u32_e32 v140, 0x58000, v239
	v_add_u32_e32 v174, 0x84000, v239
	v_pk_mul_f32 v[92:93], v[92:93], v[128:129]
	v_pk_mul_f32 v[94:95], v[94:95], v[130:131]
	v_pk_mul_f32 v[84:85], v[84:85], v[132:133]
	v_pk_mul_f32 v[86:87], v[86:87], v[134:135]
	v_pk_mul_f32 v[76:77], v[76:77], v[162:163]
	v_pk_mul_f32 v[78:79], v[78:79], v[164:165]
	v_pk_mul_f32 v[68:69], v[68:69], v[166:167]
	v_pk_mul_f32 v[70:71], v[70:71], v[168:169]
	v_pk_mul_f32 v[92:93], v[92:93], v[88:89]
	v_pk_mul_f32 v[94:95], v[94:95], v[90:91]
	v_pk_mul_f32 v[84:85], v[84:85], v[80:81]
	v_pk_mul_f32 v[86:87], v[86:87], v[82:83]
	v_pk_mul_f32 v[76:77], v[76:77], v[72:73]
	v_pk_mul_f32 v[78:79], v[78:79], v[74:75]
	v_pk_mul_f32 v[68:69], v[68:69], v[64:65]
	v_pk_mul_f32 v[70:71], v[70:71], v[66:67]
	v_cvt_pk_bf16_f32 v136, v92, v93
	v_cvt_pk_bf16_f32 v137, v94, v95
	v_cvt_pk_bf16_f32 v138, v84, v85
	v_cvt_pk_bf16_f32 v139, v86, v87
	v_cvt_pk_bf16_f32 v170, v76, v77
	v_cvt_pk_bf16_f32 v171, v78, v79
	v_cvt_pk_bf16_f32 v172, v68, v69
	v_cvt_pk_bf16_f32 v173, v70, v71
	global_store_dwordx4 v140, v[136:139], s[28:29]
	global_store_dwordx4 v174, v[170:173], s[28:29]
	s_nop 1
	v_pk_mul_f32 v[60:61], v[60:61], v[228:229] op_sel_hi:[1,0]
	v_pk_mul_f32 v[62:63], v[62:63], v[228:229] op_sel_hi:[1,0]
	v_pk_mul_f32 v[52:53], v[52:53], v[228:229] op_sel_hi:[1,0]
	v_pk_mul_f32 v[54:55], v[54:55], v[228:229] op_sel_hi:[1,0]
	v_pk_mul_f32 v[44:45], v[44:45], v[230:231] op_sel_hi:[1,0]
	v_pk_mul_f32 v[46:47], v[46:47], v[230:231] op_sel_hi:[1,0]
	v_pk_mul_f32 v[36:37], v[36:37], v[230:231] op_sel_hi:[1,0]
	v_pk_mul_f32 v[38:39], v[38:39], v[230:231] op_sel_hi:[1,0]
	v_pk_mul_f32 v[128:129], v[60:61], v[236:237] op_sel_hi:[1,0]
	v_pk_mul_f32 v[130:131], v[62:63], v[236:237] op_sel_hi:[1,0]
	v_pk_mul_f32 v[132:133], v[52:53], v[236:237] op_sel_hi:[1,0]
	v_pk_mul_f32 v[134:135], v[54:55], v[236:237] op_sel_hi:[1,0]
	v_pk_mul_f32 v[162:163], v[44:45], v[236:237] op_sel_hi:[1,0]
	v_pk_mul_f32 v[164:165], v[46:47], v[236:237] op_sel_hi:[1,0]
	v_pk_mul_f32 v[166:167], v[36:37], v[236:237] op_sel_hi:[1,0]
	v_pk_mul_f32 v[168:169], v[38:39], v[236:237] op_sel_hi:[1,0]
	v_exp_f32_e32 v128, v128
	v_exp_f32_e32 v129, v129
	v_exp_f32_e32 v130, v130
	v_exp_f32_e32 v131, v131
	v_exp_f32_e32 v132, v132
	v_exp_f32_e32 v133, v133
	v_exp_f32_e32 v134, v134
	v_exp_f32_e32 v135, v135
	v_exp_f32_e32 v162, v162
	v_exp_f32_e32 v163, v163
	v_exp_f32_e32 v164, v164
	v_exp_f32_e32 v165, v165
	v_exp_f32_e32 v166, v166
	v_exp_f32_e32 v167, v167
	v_exp_f32_e32 v168, v168
	v_exp_f32_e32 v169, v169
	v_pk_mul_f32 v[56:57], v[56:57], v[228:229] op_sel_hi:[1,0]
	v_pk_mul_f32 v[58:59], v[58:59], v[228:229] op_sel_hi:[1,0]
	v_pk_mul_f32 v[48:49], v[48:49], v[228:229] op_sel_hi:[1,0]
	v_pk_mul_f32 v[50:51], v[50:51], v[228:229] op_sel_hi:[1,0]
	v_pk_mul_f32 v[40:41], v[40:41], v[230:231] op_sel_hi:[1,0]
	v_pk_mul_f32 v[42:43], v[42:43], v[230:231] op_sel_hi:[1,0]
	v_pk_mul_f32 v[32:33], v[32:33], v[230:231] op_sel_hi:[1,0]
	v_pk_mul_f32 v[34:35], v[34:35], v[230:231] op_sel_hi:[1,0]
	v_pk_add_f32 v[128:129], v[128:129], 1.0 op_sel_hi:[1,0]
	v_pk_add_f32 v[130:131], v[130:131], 1.0 op_sel_hi:[1,0]
	v_pk_add_f32 v[132:133], v[132:133], 1.0 op_sel_hi:[1,0]
	v_pk_add_f32 v[134:135], v[134:135], 1.0 op_sel_hi:[1,0]
	v_pk_add_f32 v[162:163], v[162:163], 1.0 op_sel_hi:[1,0]
	v_pk_add_f32 v[164:165], v[164:165], 1.0 op_sel_hi:[1,0]
	v_pk_add_f32 v[166:167], v[166:167], 1.0 op_sel_hi:[1,0]
	v_pk_add_f32 v[168:169], v[168:169], 1.0 op_sel_hi:[1,0]
	v_rcp_f32_e32 v128, v128
	v_rcp_f32_e32 v129, v129
	v_rcp_f32_e32 v130, v130
	v_rcp_f32_e32 v131, v131
	v_rcp_f32_e32 v132, v132
	v_rcp_f32_e32 v133, v133
	v_rcp_f32_e32 v134, v134
	v_rcp_f32_e32 v135, v135
; __device__ __forceinline__ unsigned cvt_pk_bf16(float lo, float hi) { unsigned r; asm volatile("v_cvt_pk_bf16_f32 %0, %1, %2" : "=v"(r) : "v"(lo), "v"(hi)); return r; }
; __device__ __forceinline__ float sigmoidf_(float x) { return fast_rcp(1.0f + fast_exp2(-1.4426950408889634f * x)); }
; __device__ __forceinline__ void load_rstd(const float* part, int row0, int fq, float (&rs)[2][4]) {
;     ...
;         for (int m = 0; m < 4; ++m) { const float* p = part + (size_t)(row0 + ai * HALF + m * 16) * NPART + fq * 8;
;             const f32x4 a = *(const f32x4*)p, b = *(const f32x4*)(p + 4); float s = ((a[0] + a[1]) + (a[2] + a[3])) + ((b[0] + b[1]) + (b[2] + b[3]));
;             s += __shfl_xor(s, 16); s += __shfl_xor(s, 32); rs[ai][m] = rsqrtf(s * (1.0f / D) + RMS_EPS); }
;     __device__ __forceinline__ void operator()(const f32x4 (&acc)[2][2][4][2], const Unit& u, int wr, int wc, int fr, int fq) const {
;     ...
;             for (int m = 0; m < 4; ++m) { const float sc = rs[ai][m]; f32x4 o[2];
; #pragma unroll
;                 for (int n = 0; n < 2; ++n) { const f32x4 g = acc[ai][0][m][n] * sc, up = acc[ai][1][m][n] * sc;
; #pragma unroll
;                     for (int e = 0; e < 4; ++e) o[n][e] = g[e] * sigmoidf_(g[e]) * up[e]; }
;                 u32x4 w; w.x = cvt_pk_bf16(o[0][0], o[0][1]); w.y = cvt_pk_bf16(o[0][2], o[0][3]); w.z = cvt_pk_bf16(o[1][0], o[1][1]); w.w = cvt_pk_bf16(o[1][2], o[1][3]);
;                 *(u32x4*)(O + (size_t)(row0 + ai * HALF + m * 16) * FF + col0) = w; }
	v_rcp_f32_e32 v162, v162
	v_rcp_f32_e32 v163, v163
	v_rcp_f32_e32 v164, v164
	v_rcp_f32_e32 v165, v165
	v_rcp_f32_e32 v166, v166
	v_rcp_f32_e32 v167, v167
	v_rcp_f32_e32 v168, v168
	v_rcp_f32_e32 v169, v169
	v_add_u32_e32 v140, 0x160000, v239
	v_add_u32_e32 v174, 0x18c000, v239
	v_pk_mul_f32 v[60:61], v[60:61], v[128:129]
	v_pk_mul_f32 v[62:63], v[62:63], v[130:131]
	v_pk_mul_f32 v[52:53], v[52:53], v[132:133]
	v_pk_mul_f32 v[54:55], v[54:55], v[134:135]
	v_pk_mul_f32 v[44:45], v[44:45], v[162:163]
	v_pk_mul_f32 v[46:47], v[46:47], v[164:165]
	v_pk_mul_f32 v[36:37], v[36:37], v[166:167]
	v_pk_mul_f32 v[38:39], v[38:39], v[168:169]
	v_pk_mul_f32 v[60:61], v[60:61], v[56:57]
	v_pk_mul_f32 v[62:63], v[62:63], v[58:59]
	v_pk_mul_f32 v[52:53], v[52:53], v[48:49]
	v_pk_mul_f32 v[54:55], v[54:55], v[50:51]
	v_pk_mul_f32 v[44:45], v[44:45], v[40:41]
	v_pk_mul_f32 v[46:47], v[46:47], v[42:43]
	v_pk_mul_f32 v[36:37], v[36:37], v[32:33]
	v_pk_mul_f32 v[38:39], v[38:39], v[34:35]
	v_cvt_pk_bf16_f32 v136, v60, v61
	v_cvt_pk_bf16_f32 v137, v62, v63
	v_cvt_pk_bf16_f32 v138, v52, v53
	v_cvt_pk_bf16_f32 v139, v54, v55
	v_cvt_pk_bf16_f32 v170, v44, v45
	v_cvt_pk_bf16_f32 v171, v46, v47
	v_cvt_pk_bf16_f32 v172, v36, v37
	v_cvt_pk_bf16_f32 v173, v38, v39
	global_store_dwordx4 v140, v[136:139], s[28:29]
	global_store_dwordx4 v174, v[170:173], s[28:29]
	s_nop 1
	v_pk_mul_f32 v[28:29], v[28:29], v[232:233] op_sel_hi:[1,0]
	v_pk_mul_f32 v[30:31], v[30:31], v[232:233] op_sel_hi:[1,0]
	v_pk_mul_f32 v[20:21], v[20:21], v[232:233] op_sel_hi:[1,0]
	v_pk_mul_f32 v[22:23], v[22:23], v[232:233] op_sel_hi:[1,0]
	v_pk_mul_f32 v[12:13], v[12:13], v[234:235] op_sel_hi:[1,0]
	v_pk_mul_f32 v[14:15], v[14:15], v[234:235] op_sel_hi:[1,0]
	v_pk_mul_f32 v[4:5], v[4:5], v[234:235] op_sel_hi:[1,0]
	v_pk_mul_f32 v[6:7], v[6:7], v[234:235] op_sel_hi:[1,0]
	v_pk_mul_f32 v[128:129], v[28:29], v[236:237] op_sel_hi:[1,0]
	v_pk_mul_f32 v[130:131], v[30:31], v[236:237] op_sel_hi:[1,0]
	v_pk_mul_f32 v[132:133], v[20:21], v[236:237] op_sel_hi:[1,0]
	v_pk_mul_f32 v[134:135], v[22:23], v[236:237] op_sel_hi:[1,0]
	v_pk_mul_f32 v[162:163], v[12:13], v[236:237] op_sel_hi:[1,0]
	v_pk_mul_f32 v[164:165], v[14:15], v[236:237] op_sel_hi:[1,0]
	v_pk_mul_f32 v[166:167], v[4:5], v[236:237] op_sel_hi:[1,0]
	v_pk_mul_f32 v[168:169], v[6:7], v[236:237] op_sel_hi:[1,0]
	v_exp_f32_e32 v128, v128
	v_exp_f32_e32 v129, v129
	v_exp_f32_e32 v130, v130
	v_exp_f32_e32 v131, v131
	v_exp_f32_e32 v132, v132
	v_exp_f32_e32 v133, v133
	v_exp_f32_e32 v134, v134
	v_exp_f32_e32 v135, v135
	v_exp_f32_e32 v162, v162
	v_exp_f32_e32 v163, v163
	v_exp_f32_e32 v164, v164
	v_exp_f32_e32 v165, v165
	v_exp_f32_e32 v166, v166
	v_exp_f32_e32 v167, v167
	v_exp_f32_e32 v168, v168
	v_exp_f32_e32 v169, v169
	v_pk_mul_f32 v[24:25], v[24:25], v[232:233] op_sel_hi:[1,0]
	v_pk_mul_f32 v[26:27], v[26:27], v[232:233] op_sel_hi:[1,0]
	v_pk_mul_f32 v[16:17], v[16:17], v[232:233] op_sel_hi:[1,0]
	v_pk_mul_f32 v[18:19], v[18:19], v[232:233] op_sel_hi:[1,0]
	v_pk_mul_f32 v[8:9], v[8:9], v[234:235] op_sel_hi:[1,0]
	v_pk_mul_f32 v[10:11], v[10:11], v[234:235] op_sel_hi:[1,0]
	v_pk_mul_f32 v[0:1], v[0:1], v[234:235] op_sel_hi:[1,0]
	v_pk_mul_f32 v[2:3], v[2:3], v[234:235] op_sel_hi:[1,0]
	v_pk_add_f32 v[128:129], v[128:129], 1.0 op_sel_hi:[1,0]
	v_pk_add_f32 v[130:131], v[130:131], 1.0 op_sel_hi:[1,0]
	v_pk_add_f32 v[132:133], v[132:133], 1.0 op_sel_hi:[1,0]
	v_pk_add_f32 v[134:135], v[134:135], 1.0 op_sel_hi:[1,0]
	v_pk_add_f32 v[162:163], v[162:163], 1.0 op_sel_hi:[1,0]
	v_pk_add_f32 v[164:165], v[164:165], 1.0 op_sel_hi:[1,0]
	v_pk_add_f32 v[166:167], v[166:167], 1.0 op_sel_hi:[1,0]
	v_pk_add_f32 v[168:169], v[168:169], 1.0 op_sel_hi:[1,0]
	v_rcp_f32_e32 v128, v128
	v_rcp_f32_e32 v129, v129
	v_rcp_f32_e32 v130, v130
	v_rcp_f32_e32 v131, v131
	v_rcp_f32_e32 v132, v132
	v_rcp_f32_e32 v133, v133
	v_rcp_f32_e32 v134, v134
	v_rcp_f32_e32 v135, v135
	v_rcp_f32_e32 v162, v162
	v_rcp_f32_e32 v163, v163
	v_rcp_f32_e32 v164, v164
	v_rcp_f32_e32 v165, v165
	v_rcp_f32_e32 v166, v166
	v_rcp_f32_e32 v167, v167
	v_rcp_f32_e32 v168, v168
	v_rcp_f32_e32 v169, v169
	v_add_u32_e32 v140, 0x1b8000, v239
	v_add_u32_e32 v174, 0x1e4000, v239
	v_pk_mul_f32 v[28:29], v[28:29], v[128:129]
	v_pk_mul_f32 v[30:31], v[30:31], v[130:131]
	v_pk_mul_f32 v[20:21], v[20:21], v[132:133]
	v_pk_mul_f32 v[22:23], v[22:23], v[134:135]
	v_pk_mul_f32 v[12:13], v[12:13], v[162:163]
	v_pk_mul_f32 v[14:15], v[14:15], v[164:165]
	v_pk_mul_f32 v[4:5], v[4:5], v[166:167]
	v_pk_mul_f32 v[6:7], v[6:7], v[168:169]
	v_pk_mul_f32 v[28:29], v[28:29], v[24:25]
	v_pk_mul_f32 v[30:31], v[30:31], v[26:27]
	v_pk_mul_f32 v[20:21], v[20:21], v[16:17]
	v_pk_mul_f32 v[22:23], v[22:23], v[18:19]
	v_pk_mul_f32 v[12:13], v[12:13], v[8:9]
	v_pk_mul_f32 v[14:15], v[14:15], v[10:11]
	v_pk_mul_f32 v[4:5], v[4:5], v[0:1]
	v_pk_mul_f32 v[6:7], v[6:7], v[2:3]
	v_cvt_pk_bf16_f32 v136, v28, v29
	v_cvt_pk_bf16_f32 v137, v30, v31
	v_cvt_pk_bf16_f32 v138, v20, v21
	v_cvt_pk_bf16_f32 v139, v22, v23
	v_cvt_pk_bf16_f32 v170, v12, v13
	v_cvt_pk_bf16_f32 v171, v14, v15
	v_cvt_pk_bf16_f32 v172, v4, v5
	v_cvt_pk_bf16_f32 v173, v6, v7
	global_store_dwordx4 v140, v[136:139], s[28:29]
	global_store_dwordx4 v174, v[170:173], s[28:29]
	s_cmp_lg_u64 s[2:3], 0
	s_cbranch_scc0 .Lswg_nf_SWG_LBB0_1151
	s_cmp_eq_u32 s72, s11
	s_cbranch_scc1 .Lswg_end_SWG_LBB0_1151
	s_waitcnt vmcnt(8)
	v_add_f32_e32 v188, v188, v189
	v_add_f32_e32 v190, v190, v191
	v_add_f32_e32 v192, v192, v193
	v_add_f32_e32 v194, v194, v195
	v_add_f32_e32 v196, v196, v197
	v_add_f32_e32 v198, v198, v199
	v_add_f32_e32 v200, v200, v201
	v_add_f32_e32 v202, v202, v203
	v_add_f32_e32 v188, v188, v190
	v_add_f32_e32 v192, v192, v194
	v_add_f32_e32 v196, v196, v198
	v_add_f32_e32 v200, v200, v202
	v_add_f32_e32 v188, v188, v192
	v_add_f32_e32 v196, v196, v200
	v_add_f32_e32 v188, v188, v196
	s_nop 1
	v_add_f32_dpp v192, v188, v188 quad_perm:[1,0,3,2] row_mask:0xf bank_mask:0xf
	v_fmamk_f32 v192, v192, 0x3a000000, v238
	v_rsq_f32_e32 v192, v192
	s_and_b32 s96, s99, 1
	s_xor_b32 s96, s96, 1
	s_lshl_b32 s96, s96, 10
	s_lshl_b32 s97, s95, 7
	s_add_i32 s96, s96, s97
	s_add_i32 s96, s96, 0x21000
	v_lshrrev_b32_e32 v204, 1, v220
	v_lshl_add_u32 v204, v204, 2, s96
	ds_write_b32 v204, v192
	s_and_b32 s99, s99, 1
	s_xor_b32 s99, s99, 3
	s_branch .Lswg_end_SWG_LBB0_1151
